# latent attention: softmax row sums via v_mfma_f32_4x4x4_16b_f16 ones-A accumulate instead of 72 v_add per iteration
# baseline (speedup 1.0000x reference)
.LBB0_887:
	v_add_f32_e32 v2, 0, v175
	v_add_f32_e32 v2, v176, v2
	v_add_f32_e32 v2, v177, v2
	v_add_f32_e32 v2, v178, v2
	v_add_f32_e32 v2, v179, v2
	v_add_f32_e32 v2, v180, v2
	v_add_f32_e32 v2, v181, v2
	v_add_f32_e32 v2, v182, v2
	v_add_f32_e32 v2, v183, v2
	v_add_f32_e32 v2, v184, v2
	v_add_f32_e32 v2, v185, v2
	v_add_f32_e32 v2, v186, v2
	v_add_f32_e32 v2, v187, v2
	v_add_f32_e32 v2, v188, v2
	v_add_f32_e32 v2, v189, v2
	v_add_f32_e32 v2, v190, v2
	v_add_f32_e32 v171, v14, v2
	v_exp_f32_e32 v2, v112
	v_exp_f32_e32 v4, v113
	v_exp_f32_e32 v5, v114
	v_exp_f32_e32 v14, v115
	v_add_f32_e32 v3, 0, v2
	v_exp_f32_e32 v112, v116
	v_add_f32_e32 v3, v4, v3
	v_exp_f32_e32 v113, v117
	v_add_f32_e32 v3, v5, v3
	v_exp_f32_e32 v114, v118
	v_add_f32_e32 v3, v14, v3
	v_exp_f32_e32 v115, v119
	v_add_f32_e32 v3, v112, v3
	v_exp_f32_e32 v116, v120
	v_add_f32_e32 v3, v113, v3
	v_exp_f32_e32 v117, v121
	v_add_f32_e32 v3, v114, v3
	v_exp_f32_e32 v118, v122
	v_add_f32_e32 v3, v115, v3
	v_exp_f32_e32 v119, v123
	v_add_f32_e32 v3, v116, v3
	v_exp_f32_e32 v120, v124
	v_add_f32_e32 v3, v117, v3
	v_exp_f32_e32 v121, v125
	v_add_f32_e32 v3, v118, v3
	v_exp_f32_e32 v122, v126
	v_add_f32_e32 v3, v119, v3
	v_exp_f32_e32 v123, v127
	v_add_f32_e32 v3, v120, v3
	v_add_f32_e32 v3, v121, v3
	v_add_f32_e32 v3, v122, v3
	v_add_f32_e32 v3, v123, v3
	v_add_f32_e32 v170, v15, v3
	v_cvt_pkrtz_f16_f32 v2, v2, v4
	v_cvt_pkrtz_f16_f32 v3, v5, v14
	v_cvt_pkrtz_f16_f32 v4, v112, v113
	v_cvt_pkrtz_f16_f32 v5, v114, v115
	v_mad_i64_i32 v[128:129], s[10:11], v142, s39, 0
	s_nop 0
	v_mfma_f32_32x32x16_f16 v[48:63], v[136:139], v[2:5], v[48:63]
	v_cvt_pkrtz_f16_f32 v112, v116, v117
	v_cvt_pkrtz_f16_f32 v113, v118, v119
	v_cvt_pkrtz_f16_f32 v114, v120, v121
	v_cvt_pkrtz_f16_f32 v115, v122, v123
	s_bfe_u32 s9, s28, 0x20006
	s_lshl_b32 s10, s9, 7
	s_mov_b32 s11, s59
	v_mfma_f32_32x32x16_f16 v[64:79], v[10:13], v[2:5], v[64:79]
	v_lshl_add_u64 v[2:3], v[140:141], 0, s[10:11]
	v_and_b32_e32 v4, 7, v144
	v_readlane_b32 s10, v255, 27
	v_lshlrev_b32_e32 v4, 4, v4
	v_mov_b32_e32 v5, v211
	s_add_u32 s4, s10, s4
	v_readlane_b32 s10, v255, 28
	v_mfma_f32_32x32x16_f16 v[48:63], v[132:135], v[112:115], v[48:63]
	s_mul_i32 s9, s9, 0x24000
	v_lshl_add_u64 v[2:3], v[2:3], 0, v[4:5]
	s_addc_u32 s5, s10, s5
	s_add_i32 s58, s58, s9
	v_lshl_add_u64 v[14:15], s[4:5], 0, v[2:3]
	s_lshl_b64 s[4:5], s[58:59], 1
	v_readlane_b32 s9, v255, 29
	v_mfma_f32_32x32x16_f16 v[64:79], v[6:9], v[112:115], v[64:79]
	s_waitcnt vmcnt(0)
	s_add_u32 s4, s9, s4
	v_readlane_b32 s9, v255, 30
	v_lshl_add_u64 v[2:3], v[128:129], 0, v[4:5]
	s_addc_u32 s5, s9, s5
	s_mov_b32 s12, 1
	v_lshl_add_u64 v[150:151], s[4:5], 0, v[2:3]
	s_mov_b32 s9, 1
	s_waitcnt vmcnt(0)
	s_barrier
	v_mov_b32_e32 v224, 0
	v_mov_b32_e32 v225, 0
	v_mov_b32_e32 v226, 0
	v_mov_b32_e32 v227, 0
	v_mov_b32_e32 v250, 0
	v_mov_b32_e32 v251, 0
	v_mov_b32_e32 v252, 0
	v_mov_b32_e32 v253, 0
	v_mov_b32_e32 v246, 0x3c003c00
	v_mov_b32_e32 v247, 0x3c003c00

.LBB0_892:
	v_lshl_or_b32 v172, s12, 14, v159
	v_add_u32_e32 v2, v172, v158
	ds_read_b128 v[2:5], v2 offset:4096
	ds_read_b128 v[144:147], v157 offset:49152
	s_waitcnt lgkmcnt(0)
	s_nop 0
	v_mfma_f32_32x32x16_f16 v[128:143], v[2:5], v[144:147], v[194:209]
	v_add_u32_e32 v2, v172, v160
	ds_read_b128 v[2:5], v2 offset:4096
	ds_read_b128 v[10:13], v157 offset:57344
	s_waitcnt lgkmcnt(0)
	v_mfma_f32_32x32x16_f16 v[128:143], v[2:5], v[10:13], v[128:143]
	v_max_f32_e32 v2, v81, v81
	v_max_f32_e32 v3, v80, v80
	v_max_f32_e32 v2, v3, v2
	v_max3_f32 v2, v2, v82, v83
	v_max3_f32 v2, v2, v84, v85
	v_max3_f32 v2, v2, v86, v87
	v_max3_f32 v2, v2, v88, v89
	v_max3_f32 v2, v2, v90, v91
	v_max3_f32 v2, v2, v92, v93
	v_max3_f32 v2, v2, v94, v95
	v_cmp_lt_f32_e32 vcc, s61, v2
	s_cbranch_vccz .LBB0_894
	ds_bpermute_b32 v3, v153, v2
	s_waitcnt lgkmcnt(0)
	v_max_f32_e32 v3, v3, v3
	v_max_f32_e32 v2, v2, v3
	v_max_f32_e32 v2, v2, v2
	v_max_f32_e32 v2, 0, v2
	v_exp_f32_e64 v4, -v2
	v_add_f32_e32 v169, v169, v2
	v_pk_add_f32 v[80:81], v[80:81], v[2:3] op_sel_hi:[1,0] neg_lo:[0,1] neg_hi:[0,1]
	v_pk_add_f32 v[82:83], v[82:83], v[2:3] op_sel_hi:[1,0] neg_lo:[0,1] neg_hi:[0,1]
	v_mul_f32_e32 v171, v171, v4
	v_mul_f32_e32 v224, v224, v4
	v_mul_f32_e32 v225, v225, v4
	v_mul_f32_e32 v226, v226, v4
	v_mul_f32_e32 v227, v227, v4
	v_pk_add_f32 v[84:85], v[84:85], v[2:3] op_sel_hi:[1,0] neg_lo:[0,1] neg_hi:[0,1]
	v_pk_add_f32 v[86:87], v[86:87], v[2:3] op_sel_hi:[1,0] neg_lo:[0,1] neg_hi:[0,1]
	v_pk_add_f32 v[88:89], v[88:89], v[2:3] op_sel_hi:[1,0] neg_lo:[0,1] neg_hi:[0,1]
	v_pk_add_f32 v[90:91], v[90:91], v[2:3] op_sel_hi:[1,0] neg_lo:[0,1] neg_hi:[0,1]
	v_pk_add_f32 v[92:93], v[92:93], v[2:3] op_sel_hi:[1,0] neg_lo:[0,1] neg_hi:[0,1]
	v_pk_add_f32 v[94:95], v[94:95], v[2:3] op_sel_hi:[1,0] neg_lo:[0,1] neg_hi:[0,1]
	v_sub_f32_e32 v143, v143, v2
	v_sub_f32_e32 v142, v142, v2
	v_sub_f32_e32 v141, v141, v2
	v_sub_f32_e32 v140, v140, v2
	v_sub_f32_e32 v139, v139, v2
	v_sub_f32_e32 v138, v138, v2
	v_sub_f32_e32 v137, v137, v2
	v_sub_f32_e32 v136, v136, v2
	v_sub_f32_e32 v135, v135, v2
	v_sub_f32_e32 v134, v134, v2
	v_sub_f32_e32 v133, v133, v2
	v_sub_f32_e32 v132, v132, v2
	v_sub_f32_e32 v131, v131, v2
	v_sub_f32_e32 v130, v130, v2
	v_sub_f32_e32 v129, v129, v2
	v_sub_f32_e32 v128, v128, v2
	v_pk_mul_f32 v[30:31], v[30:31], v[4:5] op_sel_hi:[1,0]
	v_pk_mul_f32 v[28:29], v[28:29], v[4:5] op_sel_hi:[1,0]
	v_pk_mul_f32 v[26:27], v[26:27], v[4:5] op_sel_hi:[1,0]
	v_pk_mul_f32 v[24:25], v[24:25], v[4:5] op_sel_hi:[1,0]
	v_pk_mul_f32 v[22:23], v[22:23], v[4:5] op_sel_hi:[1,0]
	v_pk_mul_f32 v[20:21], v[20:21], v[4:5] op_sel_hi:[1,0]
	v_pk_mul_f32 v[18:19], v[18:19], v[4:5] op_sel_hi:[1,0]
	v_pk_mul_f32 v[16:17], v[16:17], v[4:5] op_sel_hi:[1,0]
	v_pk_mul_f32 v[46:47], v[46:47], v[4:5] op_sel_hi:[1,0]
	v_pk_mul_f32 v[44:45], v[44:45], v[4:5] op_sel_hi:[1,0]
	v_pk_mul_f32 v[42:43], v[42:43], v[4:5] op_sel_hi:[1,0]
	v_pk_mul_f32 v[40:41], v[40:41], v[4:5] op_sel_hi:[1,0]
	v_pk_mul_f32 v[38:39], v[38:39], v[4:5] op_sel_hi:[1,0]
	v_pk_mul_f32 v[36:37], v[36:37], v[4:5] op_sel_hi:[1,0]
	v_pk_mul_f32 v[34:35], v[34:35], v[4:5] op_sel_hi:[1,0]
	v_pk_mul_f32 v[32:33], v[32:33], v[4:5] op_sel_hi:[1,0]
	v_sub_f32_e32 v194, v194, v2
	v_sub_f32_e32 v195, v195, v2
	v_sub_f32_e32 v196, v196, v2
	v_sub_f32_e32 v197, v197, v2
	v_sub_f32_e32 v198, v198, v2
	v_sub_f32_e32 v199, v199, v2
	v_sub_f32_e32 v200, v200, v2
	v_sub_f32_e32 v201, v201, v2
	v_sub_f32_e32 v202, v202, v2
	v_sub_f32_e32 v203, v203, v2
	v_sub_f32_e32 v204, v204, v2
	v_sub_f32_e32 v205, v205, v2
	v_sub_f32_e32 v206, v206, v2
	v_sub_f32_e32 v207, v207, v2
	v_sub_f32_e32 v208, v208, v2
	v_sub_f32_e32 v209, v209, v2
	s_nop 1
.LBB0_894:
	v_exp_f32_e32 v173, v80
	v_add_u32_e32 v80, v172, v161
	ds_read2st64_b64 v[112:115], v80 offset0:16 offset1:24
	v_add_u32_e32 v80, v172, v162
	v_exp_f32_e32 v177, v84
	v_exp_f32_e32 v178, v85
	v_exp_f32_e32 v179, v86
	v_exp_f32_e32 v180, v87
	ds_read2st64_b64 v[84:87], v80 offset0:16 offset1:24
	v_exp_f32_e32 v174, v81
	v_exp_f32_e32 v175, v82
	v_exp_f32_e32 v176, v83
	v_exp_f32_e32 v185, v92
	v_exp_f32_e32 v186, v93
	v_exp_f32_e32 v187, v94
	v_exp_f32_e32 v188, v95
	s_waitcnt lgkmcnt(0)
	v_mov_b32_e32 v92, v112
	v_mov_b32_e32 v93, v113
	v_mov_b32_e32 v94, v84
	v_mov_b32_e32 v95, v85
	v_mov_b32_e32 v84, v114
	v_mov_b32_e32 v85, v115
	v_add_u32_e32 v80, v172, v163
	ds_read2st64_b64 v[116:119], v80 offset0:16 offset1:24
	v_add_u32_e32 v80, v172, v164
	ds_read2st64_b64 v[80:83], v80 offset0:16 offset1:24
	v_cvt_pkrtz_f16_f32 v2, v173, v174
	v_cvt_pkrtz_f16_f32 v3, v175, v176
	v_cvt_pkrtz_f16_f32 v4, v177, v178
	v_cvt_pkrtz_f16_f32 v5, v179, v180
	v_exp_f32_e32 v181, v88
	v_exp_f32_e32 v182, v89
	v_mfma_f32_4x4x4_16b_f16 v[224:227], v[246:247], v[2:3], v[224:227]
	v_mfma_f32_32x32x16_f16 v[16:31], v[92:95], v[2:5], v[16:31]
	v_exp_f32_e32 v183, v90
	v_exp_f32_e32 v184, v91
	s_waitcnt lgkmcnt(0)
	v_mov_b32_e32 v88, v116
	v_mov_b32_e32 v89, v117
	v_mov_b32_e32 v90, v80
	v_mov_b32_e32 v91, v81
	v_mov_b32_e32 v80, v118
	v_mfma_f32_4x4x4_16b_f16 v[224:227], v[246:247], v[4:5], v[224:227]
	v_mfma_f32_32x32x16_f16 v[32:47], v[84:87], v[2:5], v[32:47]
	v_mov_b32_e32 v81, v119
	v_cvt_pkrtz_f16_f32 v6, v181, v182
	v_cvt_pkrtz_f16_f32 v7, v183, v184
	v_cvt_pkrtz_f16_f32 v8, v185, v186
	v_cvt_pkrtz_f16_f32 v9, v187, v188
	v_add_u32_e32 v2, v172, v156
	v_mfma_f32_4x4x4_16b_f16 v[224:227], v[246:247], v[6:7], v[224:227]
	v_mfma_f32_32x32x16_f16 v[16:31], v[88:91], v[6:9], v[16:31]
	s_nop 0
	v_mfma_f32_4x4x4_16b_f16 v[224:227], v[246:247], v[8:9], v[224:227]
	v_mfma_f32_32x32x16_f16 v[32:47], v[80:83], v[6:9], v[32:47]
	ds_read_b128 v[2:5], v2 offset:4096
	ds_read_b128 v[6:9], v154 offset:16384
	v_max_f32_e32 v189, v97, v97
	s_waitcnt lgkmcnt(0)
	v_mfma_f32_32x32x16_f16 v[112:127], v[2:5], v[6:9], v[230:245]
	v_add_u32_e32 v2, v172, v155
	ds_read_b128 v[190:193], v2 offset:4096
	ds_read_b128 v[2:5], v154 offset:24576
	s_waitcnt lgkmcnt(0)
	v_mfma_f32_32x32x16_f16 v[112:127], v[190:193], v[2:5], v[112:127]
	v_max_f32_e32 v190, v96, v96
	v_max_f32_e32 v189, v190, v189
	v_max3_f32 v189, v189, v98, v99
	v_max3_f32 v189, v189, v100, v101
	v_max3_f32 v189, v189, v102, v103
	v_max3_f32 v189, v189, v104, v105
	v_max3_f32 v189, v189, v106, v107
	v_max3_f32 v189, v189, v108, v109
	v_max3_f32 v189, v189, v110, v111
	v_cmp_lt_f32_e32 vcc, s61, v189
	s_cbranch_vccz .LBB0_896
	ds_bpermute_b32 v190, v153, v189
	s_waitcnt lgkmcnt(0)
	v_max_f32_e32 v190, v190, v190
	v_max_f32_e32 v189, v189, v190
	v_max_f32_e32 v189, v189, v189
	v_max_f32_e32 v190, 0, v189
	v_exp_f32_e64 v192, -v190
	v_add_f32_e32 v168, v168, v190
	v_pk_add_f32 v[96:97], v[96:97], v[190:191] op_sel_hi:[1,0] neg_lo:[0,1] neg_hi:[0,1]
	v_pk_add_f32 v[98:99], v[98:99], v[190:191] op_sel_hi:[1,0] neg_lo:[0,1] neg_hi:[0,1]
	v_mul_f32_e32 v170, v170, v192
	v_mul_f32_e32 v250, v250, v192
	v_mul_f32_e32 v251, v251, v192
	v_mul_f32_e32 v252, v252, v192
	v_mul_f32_e32 v253, v253, v192
	v_pk_add_f32 v[100:101], v[100:101], v[190:191] op_sel_hi:[1,0] neg_lo:[0,1] neg_hi:[0,1]
	v_pk_add_f32 v[102:103], v[102:103], v[190:191] op_sel_hi:[1,0] neg_lo:[0,1] neg_hi:[0,1]
	v_pk_add_f32 v[104:105], v[104:105], v[190:191] op_sel_hi:[1,0] neg_lo:[0,1] neg_hi:[0,1]
	v_pk_add_f32 v[106:107], v[106:107], v[190:191] op_sel_hi:[1,0] neg_lo:[0,1] neg_hi:[0,1]
	v_pk_add_f32 v[108:109], v[108:109], v[190:191] op_sel_hi:[1,0] neg_lo:[0,1] neg_hi:[0,1]
	v_pk_add_f32 v[110:111], v[110:111], v[190:191] op_sel_hi:[1,0] neg_lo:[0,1] neg_hi:[0,1]
	v_sub_f32_e32 v127, v127, v190
	v_sub_f32_e32 v126, v126, v190
	v_sub_f32_e32 v125, v125, v190
	v_sub_f32_e32 v124, v124, v190
	v_sub_f32_e32 v123, v123, v190
	v_sub_f32_e32 v122, v122, v190
	v_sub_f32_e32 v121, v121, v190
	v_sub_f32_e32 v120, v120, v190
	v_sub_f32_e32 v119, v119, v190
	v_sub_f32_e32 v118, v118, v190
	v_sub_f32_e32 v117, v117, v190
	v_sub_f32_e32 v116, v116, v190
	v_sub_f32_e32 v115, v115, v190
	v_sub_f32_e32 v114, v114, v190
	v_sub_f32_e32 v113, v113, v190
	v_sub_f32_e32 v112, v112, v190
	v_pk_mul_f32 v[62:63], v[62:63], v[192:193] op_sel_hi:[1,0]
	v_pk_mul_f32 v[60:61], v[60:61], v[192:193] op_sel_hi:[1,0]
	v_pk_mul_f32 v[58:59], v[58:59], v[192:193] op_sel_hi:[1,0]
	v_pk_mul_f32 v[56:57], v[56:57], v[192:193] op_sel_hi:[1,0]
	v_pk_mul_f32 v[54:55], v[54:55], v[192:193] op_sel_hi:[1,0]
	v_pk_mul_f32 v[52:53], v[52:53], v[192:193] op_sel_hi:[1,0]
	v_pk_mul_f32 v[50:51], v[50:51], v[192:193] op_sel_hi:[1,0]
	v_pk_mul_f32 v[48:49], v[48:49], v[192:193] op_sel_hi:[1,0]
	v_pk_mul_f32 v[78:79], v[78:79], v[192:193] op_sel_hi:[1,0]
	v_pk_mul_f32 v[76:77], v[76:77], v[192:193] op_sel_hi:[1,0]
	v_pk_mul_f32 v[74:75], v[74:75], v[192:193] op_sel_hi:[1,0]
	v_pk_mul_f32 v[72:73], v[72:73], v[192:193] op_sel_hi:[1,0]
	v_pk_mul_f32 v[70:71], v[70:71], v[192:193] op_sel_hi:[1,0]
	v_pk_mul_f32 v[68:69], v[68:69], v[192:193] op_sel_hi:[1,0]
	v_pk_mul_f32 v[66:67], v[66:67], v[192:193] op_sel_hi:[1,0]
	v_pk_mul_f32 v[64:65], v[64:65], v[192:193] op_sel_hi:[1,0]
	v_sub_f32_e32 v230, v230, v190
	v_sub_f32_e32 v231, v231, v190
	v_sub_f32_e32 v232, v232, v190
	v_sub_f32_e32 v233, v233, v190
	v_sub_f32_e32 v234, v234, v190
	v_sub_f32_e32 v235, v235, v190
	v_sub_f32_e32 v236, v236, v190
	v_sub_f32_e32 v237, v237, v190
	v_sub_f32_e32 v238, v238, v190
	v_sub_f32_e32 v239, v239, v190
	v_sub_f32_e32 v240, v240, v190
	v_sub_f32_e32 v241, v241, v190
	v_sub_f32_e32 v242, v242, v190
	v_sub_f32_e32 v243, v243, v190
	v_sub_f32_e32 v244, v244, v190
	v_sub_f32_e32 v245, v245, v190
	s_nop 1
.LBB0_896:
	v_exp_f32_e32 v96, v96
	v_exp_f32_e32 v97, v97
	v_exp_f32_e32 v98, v98
	v_exp_f32_e32 v99, v99
	v_exp_f32_e32 v100, v100
	v_exp_f32_e32 v101, v101
	v_exp_f32_e32 v102, v102
	v_exp_f32_e32 v103, v103
	v_add_u32_e32 v173, s11, v159
	v_cvt_pkrtz_f16_f32 v174, v96, v97
	v_cvt_pkrtz_f16_f32 v175, v98, v99
	v_cvt_pkrtz_f16_f32 v176, v100, v101
	v_cvt_pkrtz_f16_f32 v177, v102, v103
	v_exp_f32_e32 v104, v104
	v_exp_f32_e32 v105, v105
	v_mfma_f32_4x4x4_16b_f16 v[250:253], v[246:247], v[174:175], v[250:253]
	v_mfma_f32_32x32x16_f16 v[48:63], v[92:95], v[174:177], v[48:63]
	v_exp_f32_e32 v106, v106
	v_exp_f32_e32 v107, v107
	v_exp_f32_e32 v108, v108
	v_exp_f32_e32 v109, v109
	v_exp_f32_e32 v110, v110
	v_exp_f32_e32 v111, v111
	v_cvt_pkrtz_f16_f32 v178, v104, v105
	v_mfma_f32_4x4x4_16b_f16 v[250:253], v[246:247], v[176:177], v[250:253]
	v_mfma_f32_32x32x16_f16 v[64:79], v[84:87], v[174:177], v[64:79]
	v_add_u32_e32 v174, v173, v158
	ds_read_b128 v[174:177], v174
	v_cvt_pkrtz_f16_f32 v179, v106, v107
	v_cvt_pkrtz_f16_f32 v180, v108, v109
	v_cvt_pkrtz_f16_f32 v181, v110, v111
	s_nop 1
	v_mfma_f32_4x4x4_16b_f16 v[250:253], v[246:247], v[178:179], v[250:253]
	v_mfma_f32_32x32x16_f16 v[64:79], v[80:83], v[178:181], v[64:79]
	s_nop 0
	v_mfma_f32_4x4x4_16b_f16 v[250:253], v[246:247], v[180:181], v[250:253]
	v_mfma_f32_32x32x16_f16 v[48:63], v[88:91], v[178:181], v[48:63]
	v_add_u32_e32 v178, v173, v160
	s_waitcnt lgkmcnt(0)
	s_nop 0
	v_mfma_f32_32x32x16_f16 v[80:95], v[174:177], v[144:147], v[194:209]
	ds_read_b128 v[144:147], v178
	s_waitcnt lgkmcnt(0)
	v_mfma_f32_32x32x16_f16 v[80:95], v[144:147], v[10:13], v[80:95]
	v_max_f32_e32 v10, v129, v129
	v_max_f32_e32 v11, v128, v128
	v_max_f32_e32 v10, v11, v10
	v_max3_f32 v10, v10, v130, v131
	v_max3_f32 v10, v10, v132, v133
	v_max3_f32 v10, v10, v134, v135
	v_max3_f32 v10, v10, v136, v137
	v_max3_f32 v10, v10, v138, v139
	v_max3_f32 v10, v10, v140, v141
	v_max3_f32 v10, v10, v142, v143
	v_cmp_lt_f32_e32 vcc, s61, v10
	s_cbranch_vccz .LBB0_898
	ds_bpermute_b32 v11, v153, v10
	s_waitcnt lgkmcnt(0)
	v_max_f32_e32 v11, v11, v11
	v_max_f32_e32 v10, v10, v11
	v_max_f32_e32 v10, v10, v10
	v_max_f32_e32 v10, 0, v10
	v_exp_f32_e64 v12, -v10
	v_add_f32_e32 v169, v169, v10
	v_pk_add_f32 v[128:129], v[128:129], v[10:11] op_sel_hi:[1,0] neg_lo:[0,1] neg_hi:[0,1]
	v_pk_add_f32 v[130:131], v[130:131], v[10:11] op_sel_hi:[1,0] neg_lo:[0,1] neg_hi:[0,1]
	v_mul_f32_e32 v171, v171, v12
	v_mul_f32_e32 v224, v224, v12
	v_mul_f32_e32 v225, v225, v12
	v_mul_f32_e32 v226, v226, v12
	v_mul_f32_e32 v227, v227, v12
	v_pk_add_f32 v[132:133], v[132:133], v[10:11] op_sel_hi:[1,0] neg_lo:[0,1] neg_hi:[0,1]
	v_pk_add_f32 v[134:135], v[134:135], v[10:11] op_sel_hi:[1,0] neg_lo:[0,1] neg_hi:[0,1]
	v_pk_add_f32 v[136:137], v[136:137], v[10:11] op_sel_hi:[1,0] neg_lo:[0,1] neg_hi:[0,1]
	v_pk_add_f32 v[138:139], v[138:139], v[10:11] op_sel_hi:[1,0] neg_lo:[0,1] neg_hi:[0,1]
	v_pk_add_f32 v[140:141], v[140:141], v[10:11] op_sel_hi:[1,0] neg_lo:[0,1] neg_hi:[0,1]
	v_pk_add_f32 v[142:143], v[142:143], v[10:11] op_sel_hi:[1,0] neg_lo:[0,1] neg_hi:[0,1]
	v_sub_f32_e32 v95, v95, v10
	v_sub_f32_e32 v94, v94, v10
	v_sub_f32_e32 v93, v93, v10
	v_sub_f32_e32 v92, v92, v10
	v_sub_f32_e32 v91, v91, v10
	v_sub_f32_e32 v90, v90, v10
	v_sub_f32_e32 v89, v89, v10
	v_sub_f32_e32 v88, v88, v10
	v_sub_f32_e32 v87, v87, v10
	v_sub_f32_e32 v86, v86, v10
	v_sub_f32_e32 v85, v85, v10
	v_sub_f32_e32 v84, v84, v10
	v_sub_f32_e32 v83, v83, v10
	v_sub_f32_e32 v82, v82, v10
	v_sub_f32_e32 v81, v81, v10
	v_sub_f32_e32 v80, v80, v10
	v_pk_mul_f32 v[30:31], v[30:31], v[12:13] op_sel_hi:[1,0]
	v_pk_mul_f32 v[28:29], v[28:29], v[12:13] op_sel_hi:[1,0]
	v_pk_mul_f32 v[26:27], v[26:27], v[12:13] op_sel_hi:[1,0]
	v_pk_mul_f32 v[24:25], v[24:25], v[12:13] op_sel_hi:[1,0]
	v_pk_mul_f32 v[22:23], v[22:23], v[12:13] op_sel_hi:[1,0]
	v_pk_mul_f32 v[20:21], v[20:21], v[12:13] op_sel_hi:[1,0]
	v_pk_mul_f32 v[18:19], v[18:19], v[12:13] op_sel_hi:[1,0]
	v_pk_mul_f32 v[16:17], v[16:17], v[12:13] op_sel_hi:[1,0]
	v_pk_mul_f32 v[46:47], v[46:47], v[12:13] op_sel_hi:[1,0]
	v_pk_mul_f32 v[44:45], v[44:45], v[12:13] op_sel_hi:[1,0]
	v_pk_mul_f32 v[42:43], v[42:43], v[12:13] op_sel_hi:[1,0]
	v_pk_mul_f32 v[40:41], v[40:41], v[12:13] op_sel_hi:[1,0]
	v_pk_mul_f32 v[38:39], v[38:39], v[12:13] op_sel_hi:[1,0]
	v_pk_mul_f32 v[36:37], v[36:37], v[12:13] op_sel_hi:[1,0]
	v_pk_mul_f32 v[34:35], v[34:35], v[12:13] op_sel_hi:[1,0]
	v_pk_mul_f32 v[32:33], v[32:33], v[12:13] op_sel_hi:[1,0]
	v_sub_f32_e32 v194, v194, v10
	v_sub_f32_e32 v195, v195, v10
	v_sub_f32_e32 v196, v196, v10
	v_sub_f32_e32 v197, v197, v10
	v_sub_f32_e32 v198, v198, v10
	v_sub_f32_e32 v199, v199, v10
	v_sub_f32_e32 v200, v200, v10
	v_sub_f32_e32 v201, v201, v10
	v_sub_f32_e32 v202, v202, v10
	v_sub_f32_e32 v203, v203, v10
	v_sub_f32_e32 v204, v204, v10
	v_sub_f32_e32 v205, v205, v10
	v_sub_f32_e32 v206, v206, v10
	v_sub_f32_e32 v207, v207, v10
	v_sub_f32_e32 v208, v208, v10
	v_sub_f32_e32 v209, v209, v10
	s_nop 1
.LBB0_898:
	v_mov_b32_e32 v144, v170
	v_add_u32_e32 v10, v172, v166
	ds_read2st64_b64 v[104:107], v10 offset0:16 offset1:24
	v_add_u32_e32 v10, v172, v167
	v_exp_f32_e32 v145, v128
	v_exp_f32_e32 v146, v129
	v_exp_f32_e32 v147, v130
	v_exp_f32_e32 v170, v131
	ds_read2st64_b64 v[128:131], v10 offset0:16 offset1:24
	v_exp_f32_e32 v174, v132
	v_exp_f32_e32 v175, v133
	v_exp_f32_e32 v176, v134
	v_exp_f32_e32 v177, v135
	v_exp_f32_e32 v178, v136
	v_exp_f32_e32 v179, v137
	v_exp_f32_e32 v180, v138
	v_exp_f32_e32 v181, v139
	s_waitcnt lgkmcnt(0)
	v_mov_b32_e32 v136, v104
	v_mov_b32_e32 v137, v105
	v_mov_b32_e32 v138, v128
	v_mov_b32_e32 v139, v129
	v_mov_b32_e32 v128, v106
	v_mov_b32_e32 v129, v107
	v_add_u32_e32 v10, v172, v1
	ds_read2st64_b64 v[108:111], v10 offset0:16 offset1:24
	v_add_u32_e32 v10, v172, v165
	ds_read2st64_b64 v[10:13], v10 offset0:16 offset1:24
	v_cvt_pkrtz_f16_f32 v96, v145, v146
	v_cvt_pkrtz_f16_f32 v97, v147, v170
	v_cvt_pkrtz_f16_f32 v98, v174, v175
	v_cvt_pkrtz_f16_f32 v99, v176, v177
	v_add_u32_e32 v172, v173, v155
	v_add_u32_e32 v173, v173, v156
	v_mfma_f32_4x4x4_16b_f16 v[224:227], v[246:247], v[96:97], v[224:227]
	v_mfma_f32_32x32x16_f16 v[16:31], v[136:139], v[96:99], v[16:31]
	ds_read_b128 v[182:185], v173
	v_exp_f32_e32 v140, v140
	v_exp_f32_e32 v141, v141
	v_exp_f32_e32 v142, v142
	v_exp_f32_e32 v143, v143
	s_waitcnt lgkmcnt(0)
	v_mov_b32_e32 v132, v108
	v_mov_b32_e32 v133, v109
	v_mfma_f32_4x4x4_16b_f16 v[224:227], v[246:247], v[98:99], v[224:227]
	v_mfma_f32_32x32x16_f16 v[32:47], v[128:131], v[96:99], v[32:47]
	v_mov_b32_e32 v134, v10
	v_mov_b32_e32 v135, v11
	v_mov_b32_e32 v10, v110
	v_mov_b32_e32 v11, v111
	v_cvt_pkrtz_f16_f32 v100, v178, v179
	v_cvt_pkrtz_f16_f32 v101, v180, v181
	v_cvt_pkrtz_f16_f32 v102, v140, v141
	v_cvt_pkrtz_f16_f32 v103, v142, v143
	v_mfma_f32_4x4x4_16b_f16 v[224:227], v[246:247], v[100:101], v[224:227]
	s_nop 0
	v_mfma_f32_32x32x16_f16 v[16:31], v[132:135], v[100:103], v[16:31]
	s_nop 0
	v_mfma_f32_4x4x4_16b_f16 v[224:227], v[246:247], v[102:103], v[224:227]
	v_mfma_f32_32x32x16_f16 v[32:47], v[10:13], v[100:103], v[32:47]
	s_nop 1
	v_mfma_f32_32x32x16_f16 v[96:111], v[182:185], v[6:9], v[230:245]
	ds_read_b128 v[6:9], v172
	s_waitcnt lgkmcnt(0)
	v_mfma_f32_32x32x16_f16 v[96:111], v[6:9], v[2:5], v[96:111]
	v_max_f32_e32 v2, v113, v113
	v_max_f32_e32 v3, v112, v112
	v_max_f32_e32 v2, v3, v2
	v_max3_f32 v2, v2, v114, v115
	v_max3_f32 v2, v2, v116, v117
	v_max3_f32 v2, v2, v118, v119
	v_max3_f32 v2, v2, v120, v121
	v_max3_f32 v2, v2, v122, v123
	v_max3_f32 v2, v2, v124, v125
	v_max3_f32 v2, v2, v126, v127
	v_cmp_lt_f32_e32 vcc, s61, v2
	s_cbranch_vccz .LBB0_900
	ds_bpermute_b32 v3, v153, v2
	s_waitcnt lgkmcnt(0)
	v_max_f32_e32 v3, v3, v3
	v_max_f32_e32 v2, v2, v3
	v_max_f32_e32 v2, v2, v2
	v_max_f32_e32 v2, 0, v2
	v_exp_f32_e64 v4, -v2
	v_add_f32_e32 v168, v168, v2
	v_pk_add_f32 v[112:113], v[112:113], v[2:3] op_sel_hi:[1,0] neg_lo:[0,1] neg_hi:[0,1]
	v_pk_add_f32 v[114:115], v[114:115], v[2:3] op_sel_hi:[1,0] neg_lo:[0,1] neg_hi:[0,1]
	v_mul_f32_e32 v144, v144, v4
	v_mul_f32_e32 v250, v250, v4
	v_mul_f32_e32 v251, v251, v4
	v_mul_f32_e32 v252, v252, v4
	v_mul_f32_e32 v253, v253, v4
	v_pk_add_f32 v[116:117], v[116:117], v[2:3] op_sel_hi:[1,0] neg_lo:[0,1] neg_hi:[0,1]
	v_pk_add_f32 v[118:119], v[118:119], v[2:3] op_sel_hi:[1,0] neg_lo:[0,1] neg_hi:[0,1]
	v_pk_add_f32 v[120:121], v[120:121], v[2:3] op_sel_hi:[1,0] neg_lo:[0,1] neg_hi:[0,1]
	v_pk_add_f32 v[122:123], v[122:123], v[2:3] op_sel_hi:[1,0] neg_lo:[0,1] neg_hi:[0,1]
	v_pk_add_f32 v[124:125], v[124:125], v[2:3] op_sel_hi:[1,0] neg_lo:[0,1] neg_hi:[0,1]
	v_pk_add_f32 v[126:127], v[126:127], v[2:3] op_sel_hi:[1,0] neg_lo:[0,1] neg_hi:[0,1]
	v_sub_f32_e32 v111, v111, v2
	v_sub_f32_e32 v110, v110, v2
	v_sub_f32_e32 v109, v109, v2
	v_sub_f32_e32 v108, v108, v2
	v_sub_f32_e32 v107, v107, v2
	v_sub_f32_e32 v106, v106, v2
	v_sub_f32_e32 v105, v105, v2
	v_sub_f32_e32 v104, v104, v2
	v_sub_f32_e32 v103, v103, v2
	v_sub_f32_e32 v102, v102, v2
	v_sub_f32_e32 v101, v101, v2
	v_sub_f32_e32 v100, v100, v2
	v_sub_f32_e32 v99, v99, v2
	v_sub_f32_e32 v98, v98, v2
	v_sub_f32_e32 v97, v97, v2
	v_sub_f32_e32 v96, v96, v2
	v_pk_mul_f32 v[62:63], v[62:63], v[4:5] op_sel_hi:[1,0]
	v_pk_mul_f32 v[60:61], v[60:61], v[4:5] op_sel_hi:[1,0]
	v_pk_mul_f32 v[58:59], v[58:59], v[4:5] op_sel_hi:[1,0]
	v_pk_mul_f32 v[56:57], v[56:57], v[4:5] op_sel_hi:[1,0]
	v_pk_mul_f32 v[54:55], v[54:55], v[4:5] op_sel_hi:[1,0]
	v_pk_mul_f32 v[52:53], v[52:53], v[4:5] op_sel_hi:[1,0]
	v_pk_mul_f32 v[50:51], v[50:51], v[4:5] op_sel_hi:[1,0]
	v_pk_mul_f32 v[48:49], v[48:49], v[4:5] op_sel_hi:[1,0]
	v_pk_mul_f32 v[78:79], v[78:79], v[4:5] op_sel_hi:[1,0]
	v_pk_mul_f32 v[76:77], v[76:77], v[4:5] op_sel_hi:[1,0]
	v_pk_mul_f32 v[74:75], v[74:75], v[4:5] op_sel_hi:[1,0]
	v_pk_mul_f32 v[72:73], v[72:73], v[4:5] op_sel_hi:[1,0]
	v_pk_mul_f32 v[70:71], v[70:71], v[4:5] op_sel_hi:[1,0]
	v_pk_mul_f32 v[68:69], v[68:69], v[4:5] op_sel_hi:[1,0]
	v_pk_mul_f32 v[66:67], v[66:67], v[4:5] op_sel_hi:[1,0]
	v_pk_mul_f32 v[64:65], v[64:65], v[4:5] op_sel_hi:[1,0]
	v_sub_f32_e32 v230, v230, v2
	v_sub_f32_e32 v231, v231, v2
	v_sub_f32_e32 v232, v232, v2
	v_sub_f32_e32 v233, v233, v2
	v_sub_f32_e32 v234, v234, v2
	v_sub_f32_e32 v235, v235, v2
	v_sub_f32_e32 v236, v236, v2
	v_sub_f32_e32 v237, v237, v2
	v_sub_f32_e32 v238, v238, v2
	v_sub_f32_e32 v239, v239, v2
	v_sub_f32_e32 v240, v240, v2
	v_sub_f32_e32 v241, v241, v2
	v_sub_f32_e32 v242, v242, v2
	v_sub_f32_e32 v243, v243, v2
	v_sub_f32_e32 v244, v244, v2
	v_sub_f32_e32 v245, v245, v2
	s_nop 1
.LBB0_900:
	v_exp_f32_e32 v2, v112
	v_exp_f32_e32 v4, v113
	v_exp_f32_e32 v5, v114
	v_exp_f32_e32 v6, v115
	v_exp_f32_e32 v7, v116
	v_exp_f32_e32 v8, v117
	v_exp_f32_e32 v9, v118
	v_exp_f32_e32 v112, v119
	v_exp_f32_e32 v113, v120
	v_exp_f32_e32 v114, v121
	v_exp_f32_e32 v115, v122
	v_exp_f32_e32 v116, v123
	v_exp_f32_e32 v117, v124
	v_exp_f32_e32 v118, v125
	v_exp_f32_e32 v119, v126
	v_exp_f32_e32 v120, v127
	v_mov_b32_e32 v170, v144
	v_cvt_pkrtz_f16_f32 v2, v2, v4
	v_cvt_pkrtz_f16_f32 v3, v5, v6
	v_cvt_pkrtz_f16_f32 v4, v7, v8
	v_cvt_pkrtz_f16_f32 v5, v9, v112
	v_cvt_pkrtz_f16_f32 v6, v113, v114
	v_cvt_pkrtz_f16_f32 v7, v115, v116
	v_mfma_f32_4x4x4_16b_f16 v[250:253], v[246:247], v[2:3], v[250:253]
	v_mfma_f32_32x32x16_f16 v[48:63], v[136:139], v[2:5], v[48:63]
	v_cvt_pkrtz_f16_f32 v8, v117, v118
	v_cvt_pkrtz_f16_f32 v9, v119, v120
	s_waitcnt vmcnt(0)
	s_add_i32 s9, s9, 1
	v_lshl_add_u64 v[14:15], v[14:15], 0, s[42:43]
	v_lshl_add_u64 v[150:151], v[150:151], 0, s[66:67]
	s_cmp_lg_u32 s9, 35
	v_mfma_f32_4x4x4_16b_f16 v[250:253], v[246:247], v[4:5], v[250:253]
	v_mfma_f32_32x32x16_f16 v[64:79], v[128:131], v[2:5], v[64:79]
	s_waitcnt vmcnt(0)
	s_barrier
	v_mfma_f32_4x4x4_16b_f16 v[250:253], v[246:247], v[6:7], v[250:253]
	v_mfma_f32_32x32x16_f16 v[48:63], v[132:135], v[6:9], v[48:63]
	s_nop 0
	v_mfma_f32_4x4x4_16b_f16 v[250:253], v[246:247], v[8:9], v[250:253]
	v_mfma_f32_32x32x16_f16 v[64:79], v[10:13], v[6:9], v[64:79]
	s_cbranch_scc0 .LBB0_902
	s_mov_b32 s12, s10
	s_branch .LBB0_888
.LBB0_902:
	v_add_f32_e32 v171, v171, v224
	s_nop 1
	v_add_f32_e32 v170, v170, v250
	v_lshl_or_b32 v14, s10, 14, v159
	v_add_u32_e32 v10, v14, v158
	ds_read_b128 v[2:5], v157 offset:57344
	ds_read_b128 v[6:9], v157 offset:49152
	ds_read_b128 v[10:13], v10 offset:4096
	s_waitcnt lgkmcnt(0)
	s_nop 0
	v_mfma_f32_32x32x16_f16 v[112:127], v[10:13], v[6:9], v[194:209]
	v_add_u32_e32 v6, v14, v160
	ds_read_b128 v[6:9], v6 offset:4096
	v_max_f32_e32 v10, v81, v81
	v_max_f32_e32 v11, v80, v80
	v_max_f32_e32 v10, v11, v10
	v_max3_f32 v10, v10, v82, v83
	v_max3_f32 v10, v10, v84, v85
	v_max3_f32 v10, v10, v86, v87
	v_max3_f32 v10, v10, v88, v89
	v_max3_f32 v10, v10, v90, v91
	v_max3_f32 v10, v10, v92, v93
	v_max3_f32 v10, v10, v94, v95
	ds_bpermute_b32 v11, v153, v10
	s_waitcnt lgkmcnt(1)
	v_mfma_f32_32x32x16_f16 v[112:127], v[6:9], v[2:5], v[112:127]
	s_waitcnt lgkmcnt(0)
	v_max_f32_e32 v2, v11, v11
	v_max_f32_e32 v2, v10, v2
	v_cmp_lt_f32_e32 vcc, s61, v2
	s_cbranch_vccz .LBB0_904
	v_max_f32_e32 v2, v2, v2
	v_max_f32_e32 v2, 0, v2
	v_exp_f32_e64 v4, -v2
	v_pk_add_f32 v[80:81], v[80:81], v[2:3] op_sel_hi:[1,0] neg_lo:[0,1] neg_hi:[0,1]
	v_pk_add_f32 v[82:83], v[82:83], v[2:3] op_sel_hi:[1,0] neg_lo:[0,1] neg_hi:[0,1]
	v_pk_add_f32 v[84:85], v[84:85], v[2:3] op_sel_hi:[1,0] neg_lo:[0,1] neg_hi:[0,1]
	v_mul_f32_e32 v171, v171, v4
	v_pk_add_f32 v[86:87], v[86:87], v[2:3] op_sel_hi:[1,0] neg_lo:[0,1] neg_hi:[0,1]
	v_pk_add_f32 v[88:89], v[88:89], v[2:3] op_sel_hi:[1,0] neg_lo:[0,1] neg_hi:[0,1]
	v_pk_add_f32 v[90:91], v[90:91], v[2:3] op_sel_hi:[1,0] neg_lo:[0,1] neg_hi:[0,1]
	v_pk_add_f32 v[92:93], v[92:93], v[2:3] op_sel_hi:[1,0] neg_lo:[0,1] neg_hi:[0,1]
	v_pk_add_f32 v[94:95], v[94:95], v[2:3] op_sel_hi:[1,0] neg_lo:[0,1] neg_hi:[0,1]
	v_sub_f32_e32 v127, v127, v2
	v_sub_f32_e32 v126, v126, v2
	v_sub_f32_e32 v125, v125, v2
	v_sub_f32_e32 v124, v124, v2
	v_sub_f32_e32 v123, v123, v2
	v_sub_f32_e32 v122, v122, v2
	v_sub_f32_e32 v121, v121, v2
	v_sub_f32_e32 v120, v120, v2
	v_sub_f32_e32 v119, v119, v2
	v_sub_f32_e32 v118, v118, v2
	v_sub_f32_e32 v117, v117, v2
	v_sub_f32_e32 v116, v116, v2
	v_sub_f32_e32 v115, v115, v2
	v_sub_f32_e32 v114, v114, v2
	v_sub_f32_e32 v113, v113, v2
	v_sub_f32_e32 v112, v112, v2
	v_pk_mul_f32 v[30:31], v[30:31], v[4:5] op_sel_hi:[1,0]
	v_pk_mul_f32 v[28:29], v[28:29], v[4:5] op_sel_hi:[1,0]
	v_pk_mul_f32 v[26:27], v[26:27], v[4:5] op_sel_hi:[1,0]
	v_pk_mul_f32 v[24:25], v[24:25], v[4:5] op_sel_hi:[1,0]
	v_pk_mul_f32 v[22:23], v[22:23], v[4:5] op_sel_hi:[1,0]
	v_pk_mul_f32 v[20:21], v[20:21], v[4:5] op_sel_hi:[1,0]
	v_pk_mul_f32 v[18:19], v[18:19], v[4:5] op_sel_hi:[1,0]
	v_pk_mul_f32 v[16:17], v[16:17], v[4:5] op_sel_hi:[1,0]
	v_pk_mul_f32 v[46:47], v[46:47], v[4:5] op_sel_hi:[1,0]
	v_pk_mul_f32 v[44:45], v[44:45], v[4:5] op_sel_hi:[1,0]
	v_pk_mul_f32 v[42:43], v[42:43], v[4:5] op_sel_hi:[1,0]
	v_pk_mul_f32 v[40:41], v[40:41], v[4:5] op_sel_hi:[1,0]
	v_pk_mul_f32 v[38:39], v[38:39], v[4:5] op_sel_hi:[1,0]
	v_pk_mul_f32 v[36:37], v[36:37], v[4:5] op_sel_hi:[1,0]
	v_pk_mul_f32 v[34:35], v[34:35], v[4:5] op_sel_hi:[1,0]
	v_pk_mul_f32 v[32:33], v[32:33], v[4:5] op_sel_hi:[1,0]
